# scan1 inner loop unrolled by two: 32 loads issued before the first 8-step group is consumed (halves the serialized load round trips)
# speedup vs baseline: 1.0047x; 1.0047x over previous
; DI float bf1(const bf16_t* p) { return __uint_as_float((unsigned)(*(GAS const bf16_t*)p) << 16); }
; DI int obid() { int b = blockIdx.x; asm volatile("" : "+s"(b)); return b; }
; DI void phase_scan1(const bf16_t* A, const bf16_t* U, float* agg) {
;     ...
;     for (int it = obid(); it < 256; it += gridDim.x) {
;         const int b = it >> 4, c = it & 15; const size_t base = ((size_t)b * TT + (size_t)c * 257) * 512 + ch;
;         float Pl = 0.f, S = 0.f;
;         for (int s0 = 0; s0 < 256; s0 += 8) {
;             float a[8], u[8];
; #pragma unroll
;             for (int e = 0; e < 8; ++e) { a[e] = bf1(A + base + (size_t)(s0 + e) * 512); u[e] = bf1(U + base + (size_t)(s0 + e) * 512); }
; #pragma unroll
;             for (int e = 0; e < 8; ++e) { S = __expf(a[e]) * S + u[e]; Pl += a[e]; }
;         }
;         { const float a = bf1(A + base + (size_t)256 * 512), u = bf1(U + base + (size_t)256 * 512); S = __expf(a) * S + u; Pl += a; }
;         agg[((size_t)it * 512 + ch) * 2] = __expf(Pl); agg[((size_t)it * 512 + ch) * 2 + 1] = S;
;     }
.LBB0_132:
	v_add_co_u32_e32 v8, vcc, 0xf7f7f000, v6
	global_load_ushort v14, v[6:7], off offset:-4096
	global_load_ushort v15, v[6:7], off offset:-3072
	global_load_ushort v16, v[6:7], off offset:-2048
	global_load_ushort v17, v[6:7], off offset:-1024
	global_load_ushort v18, v[6:7], off
	v_addc_co_u32_e32 v9, vcc, -1, v7, vcc
	v_add_co_u32_e32 v10, vcc, 0xfffff000, v6
	s_add_i32 s7, s7, 8
	s_nop 0
	v_addc_co_u32_e32 v11, vcc, -1, v7, vcc
	v_add_co_u32_e32 v12, vcc, 0xf7f80000, v6
	s_waitcnt lgkmcnt(0)
	global_load_ushort v19, v[8:9], off offset:-3072
	global_load_ushort v20, v[8:9], off offset:-1024
	global_load_ushort v21, v[10:11], off offset:-3072
	global_load_ushort v22, v[10:11], off offset:-2048
	s_nop 0
	global_load_ushort v11, v[10:11], off offset:-1024
	v_addc_co_u32_e32 v13, vcc, -1, v7, vcc
	global_load_ushort v23, v[12:13], off offset:-3072
	global_load_ushort v24, v[12:13], off offset:-1024
	global_load_ushort v25, v[8:9], off
	s_nop 0
	global_load_ushort v9, v[8:9], off offset:-2048
	s_nop 0
	global_load_ushort v26, v[12:13], off
	s_nop 0
	global_load_ushort v13, v[12:13], off offset:-2048
	s_cmpk_lt_u32 s7, 0xf8
	v_lshl_add_u64 v[6:7], v[6:7], 0, s[74:75]
	v_add_co_u32_e32 v40, vcc, 0xf7f7f000, v6
	global_load_ushort v46, v[6:7], off offset:-4096
	global_load_ushort v47, v[6:7], off offset:-3072
	global_load_ushort v48, v[6:7], off offset:-2048
	global_load_ushort v49, v[6:7], off offset:-1024
	global_load_ushort v50, v[6:7], off
	v_addc_co_u32_e32 v41, vcc, -1, v7, vcc
	v_add_co_u32_e32 v42, vcc, 0xfffff000, v6
	s_add_i32 s7, s7, 8
	s_nop 0
	v_addc_co_u32_e32 v43, vcc, -1, v7, vcc
	v_add_co_u32_e32 v44, vcc, 0xf7f80000, v6
	s_waitcnt lgkmcnt(0)
	global_load_ushort v51, v[40:41], off offset:-3072
	global_load_ushort v52, v[40:41], off offset:-1024
	global_load_ushort v53, v[42:43], off offset:-3072
	global_load_ushort v54, v[42:43], off offset:-2048
	s_nop 0
	global_load_ushort v43, v[42:43], off offset:-1024
	v_addc_co_u32_e32 v45, vcc, -1, v7, vcc
	global_load_ushort v55, v[44:45], off offset:-3072
	global_load_ushort v56, v[44:45], off offset:-1024
	global_load_ushort v57, v[40:41], off
	s_nop 0
	global_load_ushort v41, v[40:41], off offset:-2048
	s_nop 0
	global_load_ushort v58, v[44:45], off
	s_nop 0
	global_load_ushort v45, v[44:45], off offset:-2048
	s_cmpk_lt_u32 s7, 0xf8
	v_lshl_add_u64 v[6:7], v[6:7], 0, s[74:75]
	s_waitcnt vmcnt(16)
	v_lshlrev_b32_e32 v27, 16, v14
	v_lshlrev_b32_e32 v8, 16, v15
	v_lshlrev_b32_e32 v10, 16, v16
	v_lshlrev_b32_e32 v12, 16, v17
	v_lshlrev_b32_e32 v14, 16, v18
	v_lshlrev_b32_e32 v15, 16, v19
	v_lshlrev_b32_e32 v17, 16, v20
	v_lshlrev_b32_e32 v19, 16, v23
	v_add_f32_e32 v5, v5, v15
	v_lshlrev_b32_e32 v29, 16, v11
	v_mul_f32_e32 v11, 0x3fb8aa3b, v15
	v_lshlrev_b32_e32 v9, 16, v9
	v_exp_f32_e32 v23, v11
	v_mul_f32_e32 v20, 0x3fb8aa3b, v9
	v_mul_f32_e32 v15, 0x3fb8aa3b, v17
	v_lshlrev_b32_e32 v11, 16, v25
	v_exp_f32_e32 v32, v20
	v_lshlrev_b32_e32 v28, 16, v21
	v_lshlrev_b32_e32 v21, 16, v24
	v_exp_f32_e32 v24, v15
	v_mul_f32_e32 v25, 0x3fb8aa3b, v11
	v_mul_f32_e32 v16, 0x3fb8aa3b, v19
	v_exp_f32_e32 v25, v25
	v_lshlrev_b32_e32 v22, 16, v22
	v_lshlrev_b32_e32 v13, 16, v13
	v_exp_f32_e32 v31, v16
	v_fmac_f32_e32 v28, v4, v23
	v_lshlrev_b32_e32 v15, 16, v26
	v_mul_f32_e32 v26, 0x3fb8aa3b, v13
	v_fmac_f32_e32 v22, v28, v32
	v_exp_f32_e32 v16, v26
	v_fmac_f32_e32 v29, v22, v24
	v_fmac_f32_e32 v27, v29, v25
	v_mul_f32_e32 v18, 0x3fb8aa3b, v21
	v_mul_f32_e32 v4, v27, v31
	v_exp_f32_e32 v18, v18
	v_pk_add_f32 v[4:5], v[4:5], v[8:9]
	v_mul_f32_e32 v30, 0x3fb8aa3b, v15
	v_pk_mul_f32 v[8:9], v[4:5], v[16:17]
	v_pk_add_f32 v[4:5], v[4:5], v[16:17]
	v_exp_f32_e32 v20, v30
	v_mov_b32_e32 v9, v5
	v_pk_add_f32 v[4:5], v[8:9], v[10:11]
	s_nop 0
	v_pk_mul_f32 v[8:9], v[4:5], v[18:19]
	v_pk_add_f32 v[4:5], v[4:5], v[18:19]
	s_nop 0
	v_mov_b32_e32 v9, v5
	v_pk_add_f32 v[4:5], v[8:9], v[12:13]
	s_nop 0
	v_pk_mul_f32 v[8:9], v[4:5], v[20:21]
	v_pk_add_f32 v[4:5], v[4:5], v[20:21]
	s_nop 0
	v_mov_b32_e32 v9, v5
	v_pk_add_f32 v[4:5], v[8:9], v[14:15]
	s_waitcnt vmcnt(0)
	v_lshlrev_b32_e32 v27, 16, v46
	v_lshlrev_b32_e32 v8, 16, v47
	v_lshlrev_b32_e32 v10, 16, v48
	v_lshlrev_b32_e32 v12, 16, v49
	v_lshlrev_b32_e32 v14, 16, v50
	v_lshlrev_b32_e32 v15, 16, v51
	v_lshlrev_b32_e32 v17, 16, v52
	v_lshlrev_b32_e32 v19, 16, v55
	v_add_f32_e32 v5, v5, v15
	v_lshlrev_b32_e32 v29, 16, v43
	v_mul_f32_e32 v11, 0x3fb8aa3b, v15
	v_lshlrev_b32_e32 v9, 16, v41
	v_exp_f32_e32 v23, v11
	v_mul_f32_e32 v20, 0x3fb8aa3b, v9
	v_mul_f32_e32 v15, 0x3fb8aa3b, v17
	v_lshlrev_b32_e32 v11, 16, v57
	v_exp_f32_e32 v32, v20
	v_lshlrev_b32_e32 v28, 16, v53
	v_lshlrev_b32_e32 v21, 16, v56
	v_exp_f32_e32 v24, v15
	v_mul_f32_e32 v25, 0x3fb8aa3b, v11
	v_mul_f32_e32 v16, 0x3fb8aa3b, v19
	v_exp_f32_e32 v25, v25
	v_lshlrev_b32_e32 v22, 16, v54
	v_lshlrev_b32_e32 v13, 16, v45
	v_exp_f32_e32 v31, v16
	v_fmac_f32_e32 v28, v4, v23
	v_lshlrev_b32_e32 v15, 16, v58
	v_mul_f32_e32 v26, 0x3fb8aa3b, v13
	v_fmac_f32_e32 v22, v28, v32
	v_exp_f32_e32 v16, v26
	v_fmac_f32_e32 v29, v22, v24
	v_fmac_f32_e32 v27, v29, v25
	v_mul_f32_e32 v18, 0x3fb8aa3b, v21
	v_mul_f32_e32 v4, v27, v31
	v_exp_f32_e32 v18, v18
	v_pk_add_f32 v[4:5], v[4:5], v[8:9]
	v_mul_f32_e32 v30, 0x3fb8aa3b, v15
	v_pk_mul_f32 v[8:9], v[4:5], v[16:17]
	v_pk_add_f32 v[4:5], v[4:5], v[16:17]
	v_exp_f32_e32 v20, v30
	v_mov_b32_e32 v9, v5
	v_pk_add_f32 v[4:5], v[8:9], v[10:11]
	s_nop 0
	v_pk_mul_f32 v[8:9], v[4:5], v[18:19]
	v_pk_add_f32 v[4:5], v[4:5], v[18:19]
	s_nop 0
	v_mov_b32_e32 v9, v5
	v_pk_add_f32 v[4:5], v[8:9], v[12:13]
	s_nop 0
	v_pk_mul_f32 v[8:9], v[4:5], v[20:21]
	v_pk_add_f32 v[4:5], v[4:5], v[20:21]
	s_nop 0
	v_mov_b32_e32 v9, v5
	v_pk_add_f32 v[4:5], v[8:9], v[14:15]
	s_cbranch_scc1 .LBB0_132
	s_and_b32 s7, s4, 15
	s_mul_hi_i32 s9, s5, 0x1010
	s_mulk_i32 s5, 0x1010
	s_mulk_i32 s7, 0x101
	s_add_u32 s8, s5, s7
	s_addc_u32 s9, s9, 0
	s_lshl_b64 s[8:9], s[8:9], 9
	v_lshl_add_u64 v[6:7], s[8:9], 0, v[0:1]
	v_lshlrev_b64 v[6:7], 1, v[6:7]
	v_lshl_add_u64 v[8:9], s[28:29], 0, v[6:7]
	s_mov_b32 s5, 0x40000
	v_add_co_u32_e32 v8, vcc, s5, v8
	v_lshl_add_u64 v[6:7], s[38:39], 0, v[6:7]
	s_nop 0
	v_addc_co_u32_e32 v9, vcc, 0, v9, vcc
	global_load_ushort v8, v[8:9], off
	v_add_co_u32_e32 v6, vcc, s5, v6
	s_ashr_i32 s5, s4, 31
	s_nop 0
	v_addc_co_u32_e32 v7, vcc, 0, v7, vcc
	global_load_ushort v9, v[6:7], off
	s_add_i32 s6, s6, s62
	s_lshl_b64 s[8:9], s[4:5], 12
	s_add_i32 s4, s4, s62
	v_lshl_add_u64 v[6:7], v[2:3], 0, s[8:9]
	s_cmpk_gt_i32 s4, 0xff
	s_waitcnt vmcnt(1)
	v_lshlrev_b32_e32 v8, 16, v8
	v_mul_f32_e32 v10, 0x3fb8aa3b, v8
	v_add_f32_e32 v5, v5, v8
	v_exp_f32_e32 v10, v10
	v_mul_f32_e32 v5, 0x3fb8aa3b, v5
	v_exp_f32_e32 v8, v5
	s_waitcnt vmcnt(0)
	v_lshlrev_b32_e32 v9, 16, v9
	v_fmac_f32_e32 v9, v4, v10
	flat_store_dwordx2 v[6:7], v[8:9]
	s_cbranch_scc0 .LBB0_131
